# v59: x_new stores of the folded epilogue issued after the panel hand-off, interleaved with the in-register normalisation
# baseline (speedup 1.0000x reference)
.Lrf_nopub:
	s_waitcnt vmcnt(0)
	v_readlane_b32 s8, v254, 61
	s_cmp_eq_u32 s8, 35
	s_cbranch_scc1 .Lrf_j1
	v_add_f32_e32 v146, 1.0, v146
	v_add_f32_e32 v147, 1.0, v147
	v_add_f32_e32 v148, 1.0, v148
	v_add_f32_e32 v149, 1.0, v149
	v_add_f32_e32 v150, 1.0, v150
	v_add_f32_e32 v151, 1.0, v151
	v_add_f32_e32 v152, 1.0, v152
	v_add_f32_e32 v153, 1.0, v153
	v_add_f32_e32 v154, 1.0, v154
	v_add_f32_e32 v155, 1.0, v155
	v_add_f32_e32 v156, 1.0, v156
	v_add_f32_e32 v157, 1.0, v157
	v_add_f32_e32 v158, 1.0, v158
	v_add_f32_e32 v159, 1.0, v159
	v_add_f32_e32 v160, 1.0, v160
	v_add_f32_e32 v161, 1.0, v161
	v_mul_f32_e32 v146, v130, v146
	v_mul_f32_e32 v147, v131, v147
	v_mul_f32_e32 v148, v132, v148
	v_mul_f32_e32 v149, v133, v149
	v_mul_f32_e32 v150, v134, v150
	v_mul_f32_e32 v151, v135, v151
	v_mul_f32_e32 v152, v136, v152
	v_mul_f32_e32 v153, v137, v153
	v_mul_f32_e32 v154, v138, v154
	v_mul_f32_e32 v155, v139, v155
	v_mul_f32_e32 v156, v140, v156
	v_mul_f32_e32 v157, v141, v157
	v_mul_f32_e32 v158, v142, v158
	v_mul_f32_e32 v159, v143, v159
	v_mul_f32_e32 v160, v144, v160
	v_mul_f32_e32 v161, v145, v161

.Lrf_bar:
	s_barrier
	global_load_dwordx4 v[200:203], v253, s[10:11] offset:0
	global_load_dwordx4 v[204:207], v253, s[10:11] offset:256
	global_load_dwordx4 v[208:211], v253, s[10:11] offset:512
	global_load_dwordx4 v[212:215], v253, s[10:11] offset:768
	global_load_dwordx4 v[216:219], v253, s[10:11] offset:2048
	global_load_dwordx4 v[220:223], v253, s[10:11] offset:2304
	global_load_dwordx4 v[240:243], v253, s[10:11] offset:2560
	global_load_dwordx4 v[244:247], v253, s[10:11] offset:2816
	v_lshl_add_u32 v251, v236, 2, s68
	v_lshlrev_b32_e32 v251, 1, v251
	v_add_u32_e32 v249, s67, v235
	v_mul_u32_u24_e32 v249, 0x210, v249
	v_add_u32_e32 v251, v251, v249
	v_add_u32_e32 v252, 0x10800, v251
	s_mov_b32 s2, 0x3a800000
	s_waitcnt vmcnt(7)
	v_add_f32_e32 v200, v200, v201
	v_add_f32_e32 v202, v202, v203
	v_add_f32_e32 v200, v200, v202
	v_fma_f32 v200, v200, s2, v167
	v_rsq_f32_e32 v200, v200
	s_waitcnt vmcnt(6)
	v_add_f32_e32 v204, v204, v205
	v_add_f32_e32 v206, v206, v207
	v_add_f32_e32 v204, v204, v206
	v_fma_f32 v204, v204, s2, v167
	v_rsq_f32_e32 v204, v204
	s_waitcnt vmcnt(5)
	v_add_f32_e32 v208, v208, v209
	v_add_f32_e32 v210, v210, v211
	v_add_f32_e32 v208, v208, v210
	v_fma_f32 v208, v208, s2, v167
	v_rsq_f32_e32 v208, v208
	s_waitcnt vmcnt(4)
	v_add_f32_e32 v212, v212, v213
	v_add_f32_e32 v214, v214, v215
	v_add_f32_e32 v212, v212, v214
	v_fma_f32 v212, v212, s2, v167
	v_rsq_f32_e32 v212, v212
	s_waitcnt vmcnt(3)
	v_add_f32_e32 v216, v216, v217
	v_add_f32_e32 v218, v218, v219
	v_add_f32_e32 v216, v216, v218
	v_fma_f32 v216, v216, s2, v167
	v_rsq_f32_e32 v216, v216
	s_waitcnt vmcnt(2)
	v_add_f32_e32 v220, v220, v221
	v_add_f32_e32 v222, v222, v223
	v_add_f32_e32 v220, v220, v222
	v_fma_f32 v220, v220, s2, v167
	v_rsq_f32_e32 v220, v220
	s_waitcnt vmcnt(1)
	v_add_f32_e32 v240, v240, v241
	v_add_f32_e32 v242, v242, v243
	v_add_f32_e32 v240, v240, v242
	v_fma_f32 v240, v240, s2, v167
	v_rsq_f32_e32 v240, v240
	s_waitcnt vmcnt(0)
	v_add_f32_e32 v244, v244, v245
	v_add_f32_e32 v246, v246, v247
	v_add_f32_e32 v244, v244, v246
	v_fma_f32 v244, v244, s2, v167
	v_rsq_f32_e32 v244, v244
	s_nop 0
	v_readlane_b32 s8, v254, 61
	s_cmp_eq_u32 s8, 35
	s_cbranch_scc1 .Lrf_fin2
	global_store_dwordx4 v248, v[126:129], s[100:101] offset:0
	global_store_dwordx4 v248, v[122:125], s[100:101] offset:64
	global_store_dwordx4 v248, v[118:121], s[100:101] offset:512
	global_store_dwordx4 v248, v[114:117], s[100:101] offset:576
	s_nop 1
	v_mul_f32_e32 v126, v126, v200
	v_mul_f32_e32 v127, v127, v200
	v_mul_f32_e32 v128, v128, v200
	v_mul_f32_e32 v129, v129, v200
	v_fma_f32 v126, v126, v146, v162
	v_fma_f32 v127, v127, v147, v163
	v_fma_f32 v128, v128, v148, v164
	v_fma_f32 v129, v129, v149, v165
	v_cvt_pk_bf16_f32 v126, v126, v127
	v_cvt_pk_bf16_f32 v127, v128, v129
	v_mul_f32_e32 v122, v122, v200
	v_mul_f32_e32 v123, v123, v200
	v_mul_f32_e32 v124, v124, v200
	v_mul_f32_e32 v125, v125, v200
	v_fma_f32 v122, v122, v150, v188
	v_fma_f32 v123, v123, v151, v189
	v_fma_f32 v124, v124, v152, v190
	v_fma_f32 v125, v125, v153, v191
	v_cvt_pk_bf16_f32 v122, v122, v123
	v_cvt_pk_bf16_f32 v123, v124, v125
	v_mul_f32_e32 v118, v118, v200
	v_mul_f32_e32 v119, v119, v200
	v_mul_f32_e32 v120, v120, v200
	v_mul_f32_e32 v121, v121, v200
	v_fma_f32 v118, v118, v154, v192
	v_fma_f32 v119, v119, v155, v193
	v_fma_f32 v120, v120, v156, v194
	v_fma_f32 v121, v121, v157, v195
	v_cvt_pk_bf16_f32 v118, v118, v119
	v_cvt_pk_bf16_f32 v119, v120, v121
	v_mul_f32_e32 v114, v114, v200
	v_mul_f32_e32 v115, v115, v200
	v_mul_f32_e32 v116, v116, v200
	v_mul_f32_e32 v117, v117, v200
	v_fma_f32 v114, v114, v158, v196
	v_fma_f32 v115, v115, v159, v197
	v_fma_f32 v116, v116, v160, v198
	v_fma_f32 v117, v117, v161, v199
	v_cvt_pk_bf16_f32 v114, v114, v115
	v_cvt_pk_bf16_f32 v115, v116, v117
	ds_write_b64 v251, v[126:127] offset:0
	ds_write_b64 v251, v[122:123] offset:32
	ds_write_b64 v251, v[118:119] offset:256
	ds_write_b64 v251, v[114:115] offset:288
	s_add_u32 s8, s100, 0x10000
	s_addc_u32 s9, s101, 0
	global_store_dwordx4 v248, v[110:113], s[8:9] offset:0
	global_store_dwordx4 v248, v[106:109], s[8:9] offset:64
	global_store_dwordx4 v248, v[102:105], s[8:9] offset:512
	global_store_dwordx4 v248, v[98:101], s[8:9] offset:576
	s_nop 1
	v_mul_f32_e32 v110, v110, v204
	v_mul_f32_e32 v111, v111, v204
	v_mul_f32_e32 v112, v112, v204
	v_mul_f32_e32 v113, v113, v204
	v_fma_f32 v110, v110, v146, v162
	v_fma_f32 v111, v111, v147, v163
	v_fma_f32 v112, v112, v148, v164
	v_fma_f32 v113, v113, v149, v165
	v_cvt_pk_bf16_f32 v110, v110, v111
	v_cvt_pk_bf16_f32 v111, v112, v113
	v_mul_f32_e32 v106, v106, v204
	v_mul_f32_e32 v107, v107, v204
	v_mul_f32_e32 v108, v108, v204
	v_mul_f32_e32 v109, v109, v204
	v_fma_f32 v106, v106, v150, v188
	v_fma_f32 v107, v107, v151, v189
	v_fma_f32 v108, v108, v152, v190
	v_fma_f32 v109, v109, v153, v191
	v_cvt_pk_bf16_f32 v106, v106, v107
	v_cvt_pk_bf16_f32 v107, v108, v109
	v_mul_f32_e32 v102, v102, v204
	v_mul_f32_e32 v103, v103, v204
	v_mul_f32_e32 v104, v104, v204
	v_mul_f32_e32 v105, v105, v204
	v_fma_f32 v102, v102, v154, v192
	v_fma_f32 v103, v103, v155, v193
	v_fma_f32 v104, v104, v156, v194
	v_fma_f32 v105, v105, v157, v195
	v_cvt_pk_bf16_f32 v102, v102, v103
	v_cvt_pk_bf16_f32 v103, v104, v105
	v_mul_f32_e32 v98, v98, v204
	v_mul_f32_e32 v99, v99, v204
	v_mul_f32_e32 v100, v100, v204
	v_mul_f32_e32 v101, v101, v204
	v_fma_f32 v98, v98, v158, v196
	v_fma_f32 v99, v99, v159, v197
	v_fma_f32 v100, v100, v160, v198
	v_fma_f32 v101, v101, v161, v199
	v_cvt_pk_bf16_f32 v98, v98, v99
	v_cvt_pk_bf16_f32 v99, v100, v101
	ds_write_b64 v251, v[110:111] offset:8448
	ds_write_b64 v251, v[106:107] offset:8480
	ds_write_b64 v251, v[102:103] offset:8704
	ds_write_b64 v251, v[98:99] offset:8736
	s_add_u32 s8, s100, 0x20000
	s_addc_u32 s9, s101, 0
	global_store_dwordx4 v248, v[94:97], s[8:9] offset:0
	global_store_dwordx4 v248, v[90:93], s[8:9] offset:64
	global_store_dwordx4 v248, v[86:89], s[8:9] offset:512
	global_store_dwordx4 v248, v[82:85], s[8:9] offset:576
	s_nop 1
	v_mul_f32_e32 v94, v94, v208
	v_mul_f32_e32 v95, v95, v208
	v_mul_f32_e32 v96, v96, v208
	v_mul_f32_e32 v97, v97, v208
	v_fma_f32 v94, v94, v146, v162
	v_fma_f32 v95, v95, v147, v163
	v_fma_f32 v96, v96, v148, v164
	v_fma_f32 v97, v97, v149, v165
	v_cvt_pk_bf16_f32 v94, v94, v95
	v_cvt_pk_bf16_f32 v95, v96, v97
	v_mul_f32_e32 v90, v90, v208
	v_mul_f32_e32 v91, v91, v208
	v_mul_f32_e32 v92, v92, v208
	v_mul_f32_e32 v93, v93, v208
	v_fma_f32 v90, v90, v150, v188
	v_fma_f32 v91, v91, v151, v189
	v_fma_f32 v92, v92, v152, v190
	v_fma_f32 v93, v93, v153, v191
	v_cvt_pk_bf16_f32 v90, v90, v91
	v_cvt_pk_bf16_f32 v91, v92, v93
	v_mul_f32_e32 v86, v86, v208
	v_mul_f32_e32 v87, v87, v208
	v_mul_f32_e32 v88, v88, v208
	v_mul_f32_e32 v89, v89, v208
	v_fma_f32 v86, v86, v154, v192
	v_fma_f32 v87, v87, v155, v193
	v_fma_f32 v88, v88, v156, v194
	v_fma_f32 v89, v89, v157, v195
	v_cvt_pk_bf16_f32 v86, v86, v87
	v_cvt_pk_bf16_f32 v87, v88, v89
	v_mul_f32_e32 v82, v82, v208
	v_mul_f32_e32 v83, v83, v208
	v_mul_f32_e32 v84, v84, v208
	v_mul_f32_e32 v85, v85, v208
	v_fma_f32 v82, v82, v158, v196
	v_fma_f32 v83, v83, v159, v197
	v_fma_f32 v84, v84, v160, v198
	v_fma_f32 v85, v85, v161, v199
	v_cvt_pk_bf16_f32 v82, v82, v83
	v_cvt_pk_bf16_f32 v83, v84, v85
	ds_write_b64 v251, v[94:95] offset:16896
	ds_write_b64 v251, v[90:91] offset:16928
	ds_write_b64 v251, v[86:87] offset:17152
	ds_write_b64 v251, v[82:83] offset:17184
	s_add_u32 s8, s100, 0x30000
	s_addc_u32 s9, s101, 0
	global_store_dwordx4 v248, v[78:81], s[8:9] offset:0
	global_store_dwordx4 v248, v[74:77], s[8:9] offset:64
	global_store_dwordx4 v248, v[70:73], s[8:9] offset:512
	global_store_dwordx4 v248, v[66:69], s[8:9] offset:576
	s_nop 1
	v_mul_f32_e32 v78, v78, v212
	v_mul_f32_e32 v79, v79, v212
	v_mul_f32_e32 v80, v80, v212
	v_mul_f32_e32 v81, v81, v212
	v_fma_f32 v78, v78, v146, v162
	v_fma_f32 v79, v79, v147, v163
	v_fma_f32 v80, v80, v148, v164
	v_fma_f32 v81, v81, v149, v165
	v_cvt_pk_bf16_f32 v78, v78, v79
	v_cvt_pk_bf16_f32 v79, v80, v81
	v_mul_f32_e32 v74, v74, v212
	v_mul_f32_e32 v75, v75, v212
	v_mul_f32_e32 v76, v76, v212
	v_mul_f32_e32 v77, v77, v212
	v_fma_f32 v74, v74, v150, v188
	v_fma_f32 v75, v75, v151, v189
	v_fma_f32 v76, v76, v152, v190
	v_fma_f32 v77, v77, v153, v191
	v_cvt_pk_bf16_f32 v74, v74, v75
	v_cvt_pk_bf16_f32 v75, v76, v77
	v_mul_f32_e32 v70, v70, v212
	v_mul_f32_e32 v71, v71, v212
	v_mul_f32_e32 v72, v72, v212
	v_mul_f32_e32 v73, v73, v212
	v_fma_f32 v70, v70, v154, v192
	v_fma_f32 v71, v71, v155, v193
	v_fma_f32 v72, v72, v156, v194
	v_fma_f32 v73, v73, v157, v195
	v_cvt_pk_bf16_f32 v70, v70, v71
	v_cvt_pk_bf16_f32 v71, v72, v73
	v_mul_f32_e32 v66, v66, v212
	v_mul_f32_e32 v67, v67, v212
	v_mul_f32_e32 v68, v68, v212
	v_mul_f32_e32 v69, v69, v212
	v_fma_f32 v66, v66, v158, v196
	v_fma_f32 v67, v67, v159, v197
	v_fma_f32 v68, v68, v160, v198
	v_fma_f32 v69, v69, v161, v199
	v_cvt_pk_bf16_f32 v66, v66, v67
	v_cvt_pk_bf16_f32 v67, v68, v69
	ds_write_b64 v251, v[78:79] offset:25344
	ds_write_b64 v251, v[74:75] offset:25376
	ds_write_b64 v251, v[70:71] offset:25600
	ds_write_b64 v251, v[66:67] offset:25632
	s_add_u32 s8, s100, 0x80000
	s_addc_u32 s9, s101, 0
	global_store_dwordx4 v248, v[62:65], s[8:9] offset:0
	global_store_dwordx4 v248, v[58:61], s[8:9] offset:64
	global_store_dwordx4 v248, v[54:57], s[8:9] offset:512
	global_store_dwordx4 v248, v[50:53], s[8:9] offset:576
	s_nop 1
	v_mul_f32_e32 v62, v62, v216
	v_mul_f32_e32 v63, v63, v216
	v_mul_f32_e32 v64, v64, v216
	v_mul_f32_e32 v65, v65, v216
	v_fma_f32 v62, v62, v146, v162
	v_fma_f32 v63, v63, v147, v163
	v_fma_f32 v64, v64, v148, v164
	v_fma_f32 v65, v65, v149, v165
	v_cvt_pk_bf16_f32 v62, v62, v63
	v_cvt_pk_bf16_f32 v63, v64, v65
	v_mul_f32_e32 v58, v58, v216
	v_mul_f32_e32 v59, v59, v216
	v_mul_f32_e32 v60, v60, v216
	v_mul_f32_e32 v61, v61, v216
	v_fma_f32 v58, v58, v150, v188
	v_fma_f32 v59, v59, v151, v189
	v_fma_f32 v60, v60, v152, v190
	v_fma_f32 v61, v61, v153, v191
	v_cvt_pk_bf16_f32 v58, v58, v59
	v_cvt_pk_bf16_f32 v59, v60, v61
	v_mul_f32_e32 v54, v54, v216
	v_mul_f32_e32 v55, v55, v216
	v_mul_f32_e32 v56, v56, v216
	v_mul_f32_e32 v57, v57, v216
	v_fma_f32 v54, v54, v154, v192
	v_fma_f32 v55, v55, v155, v193
	v_fma_f32 v56, v56, v156, v194
	v_fma_f32 v57, v57, v157, v195
	v_cvt_pk_bf16_f32 v54, v54, v55
	v_cvt_pk_bf16_f32 v55, v56, v57
	v_mul_f32_e32 v50, v50, v216
	v_mul_f32_e32 v51, v51, v216
	v_mul_f32_e32 v52, v52, v216
	v_mul_f32_e32 v53, v53, v216
	v_fma_f32 v50, v50, v158, v196
	v_fma_f32 v51, v51, v159, v197
	v_fma_f32 v52, v52, v160, v198
	v_fma_f32 v53, v53, v161, v199
	v_cvt_pk_bf16_f32 v50, v50, v51
	v_cvt_pk_bf16_f32 v51, v52, v53
	ds_write_b64 v252, v[62:63] offset:0
	ds_write_b64 v252, v[58:59] offset:32
	ds_write_b64 v252, v[54:55] offset:256
	ds_write_b64 v252, v[50:51] offset:288
	s_add_u32 s8, s100, 0x90000
	s_addc_u32 s9, s101, 0
	global_store_dwordx4 v248, v[46:49], s[8:9] offset:0
	global_store_dwordx4 v248, v[42:45], s[8:9] offset:64
	global_store_dwordx4 v248, v[38:41], s[8:9] offset:512
	global_store_dwordx4 v248, v[34:37], s[8:9] offset:576
	s_nop 1
	v_mul_f32_e32 v46, v46, v220
	v_mul_f32_e32 v47, v47, v220
	v_mul_f32_e32 v48, v48, v220
	v_mul_f32_e32 v49, v49, v220
	v_fma_f32 v46, v46, v146, v162
	v_fma_f32 v47, v47, v147, v163
	v_fma_f32 v48, v48, v148, v164
	v_fma_f32 v49, v49, v149, v165
	v_cvt_pk_bf16_f32 v46, v46, v47
	v_cvt_pk_bf16_f32 v47, v48, v49
	v_mul_f32_e32 v42, v42, v220
	v_mul_f32_e32 v43, v43, v220
	v_mul_f32_e32 v44, v44, v220
	v_mul_f32_e32 v45, v45, v220
	v_fma_f32 v42, v42, v150, v188
	v_fma_f32 v43, v43, v151, v189
	v_fma_f32 v44, v44, v152, v190
	v_fma_f32 v45, v45, v153, v191
	v_cvt_pk_bf16_f32 v42, v42, v43
	v_cvt_pk_bf16_f32 v43, v44, v45
	v_mul_f32_e32 v38, v38, v220
	v_mul_f32_e32 v39, v39, v220
	v_mul_f32_e32 v40, v40, v220
	v_mul_f32_e32 v41, v41, v220
	v_fma_f32 v38, v38, v154, v192
	v_fma_f32 v39, v39, v155, v193
	v_fma_f32 v40, v40, v156, v194
	v_fma_f32 v41, v41, v157, v195
	v_cvt_pk_bf16_f32 v38, v38, v39
	v_cvt_pk_bf16_f32 v39, v40, v41
	v_mul_f32_e32 v34, v34, v220
	v_mul_f32_e32 v35, v35, v220
	v_mul_f32_e32 v36, v36, v220
	v_mul_f32_e32 v37, v37, v220
	v_fma_f32 v34, v34, v158, v196
	v_fma_f32 v35, v35, v159, v197
	v_fma_f32 v36, v36, v160, v198
	v_fma_f32 v37, v37, v161, v199
	v_cvt_pk_bf16_f32 v34, v34, v35
	v_cvt_pk_bf16_f32 v35, v36, v37
	ds_write_b64 v252, v[46:47] offset:8448
	ds_write_b64 v252, v[42:43] offset:8480
	ds_write_b64 v252, v[38:39] offset:8704
	ds_write_b64 v252, v[34:35] offset:8736
	s_add_u32 s8, s100, 0xa0000
	s_addc_u32 s9, s101, 0
	global_store_dwordx4 v248, v[30:33], s[8:9] offset:0
	global_store_dwordx4 v248, v[26:29], s[8:9] offset:64
	global_store_dwordx4 v248, v[22:25], s[8:9] offset:512
	global_store_dwordx4 v248, v[18:21], s[8:9] offset:576
	s_nop 1
	v_mul_f32_e32 v30, v30, v240
	v_mul_f32_e32 v31, v31, v240
	v_mul_f32_e32 v32, v32, v240
	v_mul_f32_e32 v33, v33, v240
	v_fma_f32 v30, v30, v146, v162
	v_fma_f32 v31, v31, v147, v163
	v_fma_f32 v32, v32, v148, v164
	v_fma_f32 v33, v33, v149, v165
	v_cvt_pk_bf16_f32 v30, v30, v31
	v_cvt_pk_bf16_f32 v31, v32, v33
	v_mul_f32_e32 v26, v26, v240
	v_mul_f32_e32 v27, v27, v240
	v_mul_f32_e32 v28, v28, v240
	v_mul_f32_e32 v29, v29, v240
	v_fma_f32 v26, v26, v150, v188
	v_fma_f32 v27, v27, v151, v189
	v_fma_f32 v28, v28, v152, v190
	v_fma_f32 v29, v29, v153, v191
	v_cvt_pk_bf16_f32 v26, v26, v27
	v_cvt_pk_bf16_f32 v27, v28, v29
	v_mul_f32_e32 v22, v22, v240
	v_mul_f32_e32 v23, v23, v240
	v_mul_f32_e32 v24, v24, v240
	v_mul_f32_e32 v25, v25, v240
	v_fma_f32 v22, v22, v154, v192
	v_fma_f32 v23, v23, v155, v193
	v_fma_f32 v24, v24, v156, v194
	v_fma_f32 v25, v25, v157, v195
	v_cvt_pk_bf16_f32 v22, v22, v23
	v_cvt_pk_bf16_f32 v23, v24, v25
	v_mul_f32_e32 v18, v18, v240
	v_mul_f32_e32 v19, v19, v240
	v_mul_f32_e32 v20, v20, v240
	v_mul_f32_e32 v21, v21, v240
	v_fma_f32 v18, v18, v158, v196
	v_fma_f32 v19, v19, v159, v197
	v_fma_f32 v20, v20, v160, v198
	v_fma_f32 v21, v21, v161, v199
	v_cvt_pk_bf16_f32 v18, v18, v19
	v_cvt_pk_bf16_f32 v19, v20, v21
	ds_write_b64 v252, v[30:31] offset:16896
	ds_write_b64 v252, v[26:27] offset:16928
	ds_write_b64 v252, v[22:23] offset:17152
	ds_write_b64 v252, v[18:19] offset:17184
	s_add_u32 s8, s100, 0xb0000
	s_addc_u32 s9, s101, 0
	global_store_dwordx4 v248, v[14:17], s[8:9] offset:0
	global_store_dwordx4 v248, v[10:13], s[8:9] offset:64
	global_store_dwordx4 v248, v[6:9], s[8:9] offset:512
	global_store_dwordx4 v248, v[2:5], s[8:9] offset:576
	s_nop 1
	v_mul_f32_e32 v14, v14, v244
	v_mul_f32_e32 v15, v15, v244
	v_mul_f32_e32 v16, v16, v244
	v_mul_f32_e32 v17, v17, v244
	v_fma_f32 v14, v14, v146, v162
	v_fma_f32 v15, v15, v147, v163
	v_fma_f32 v16, v16, v148, v164
	v_fma_f32 v17, v17, v149, v165
	v_cvt_pk_bf16_f32 v14, v14, v15
	v_cvt_pk_bf16_f32 v15, v16, v17
	v_mul_f32_e32 v10, v10, v244
	v_mul_f32_e32 v11, v11, v244
	v_mul_f32_e32 v12, v12, v244
	v_mul_f32_e32 v13, v13, v244
	v_fma_f32 v10, v10, v150, v188
	v_fma_f32 v11, v11, v151, v189
	v_fma_f32 v12, v12, v152, v190
	v_fma_f32 v13, v13, v153, v191
	v_cvt_pk_bf16_f32 v10, v10, v11
	v_cvt_pk_bf16_f32 v11, v12, v13
	v_mul_f32_e32 v6, v6, v244
	v_mul_f32_e32 v7, v7, v244
	v_mul_f32_e32 v8, v8, v244
	v_mul_f32_e32 v9, v9, v244
	v_fma_f32 v6, v6, v154, v192
	v_fma_f32 v7, v7, v155, v193
	v_fma_f32 v8, v8, v156, v194
	v_fma_f32 v9, v9, v157, v195
	v_cvt_pk_bf16_f32 v6, v6, v7
	v_cvt_pk_bf16_f32 v7, v8, v9
	v_mul_f32_e32 v2, v2, v244
	v_mul_f32_e32 v3, v3, v244
	v_mul_f32_e32 v4, v4, v244
	v_mul_f32_e32 v5, v5, v244
	v_fma_f32 v2, v2, v158, v196
	v_fma_f32 v3, v3, v159, v197
	v_fma_f32 v4, v4, v160, v198
	v_fma_f32 v5, v5, v161, v199
	v_cvt_pk_bf16_f32 v2, v2, v3
	v_cvt_pk_bf16_f32 v3, v4, v5
	ds_write_b64 v252, v[14:15] offset:25344
	ds_write_b64 v252, v[10:11] offset:25376
	ds_write_b64 v252, v[6:7] offset:25600
	ds_write_b64 v252, v[2:3] offset:25632
	v_lshl_add_u32 v249, v236, 4, v235
	v_lshrrev_b32_e32 v250, 5, v249
	v_and_b32_e32 v249, 31, v249
	v_lshlrev_b32_e32 v249, 4, v249
	v_lshl_add_u32 v250, s3, 5, v250
	v_mul_u32_u24_e32 v251, 0x210, v250
	v_add_u32_e32 v251, v251, v249
	v_lshl_add_u32 v248, v250, 11, v249
	v_readlane_b32 s12, v255, 9
	v_readlane_b32 s13, v255, 10
	s_lshl_b32 s2, s17, 19
	s_lshl_b32 s8, s48, 9
	s_add_i32 s2, s2, s8
	s_add_u32 s12, s12, s2
	s_addc_u32 s13, s13, 0
	s_waitcnt lgkmcnt(0)
	s_barrier
	ds_read_b128 v[2:5], v251 offset:0
	ds_read_b128 v[6:9], v251 offset:1056
	ds_read_b128 v[10:13], v251 offset:2112
	ds_read_b128 v[14:17], v251 offset:3168
	ds_read_b128 v[18:21], v251 offset:4224
	ds_read_b128 v[22:25], v251 offset:5280
	ds_read_b128 v[26:29], v251 offset:6336
	ds_read_b128 v[30:33], v251 offset:7392
	ds_read_b128 v[34:37], v251 offset:8448
	ds_read_b128 v[38:41], v251 offset:9504
	ds_read_b128 v[42:45], v251 offset:10560
	ds_read_b128 v[46:49], v251 offset:11616
	ds_read_b128 v[50:53], v251 offset:12672
	ds_read_b128 v[54:57], v251 offset:13728
	ds_read_b128 v[58:61], v251 offset:14784
	ds_read_b128 v[62:65], v251 offset:15840
	s_waitcnt lgkmcnt(15)
	global_store_dwordx4 v248, v[2:5], s[12:13]
	s_waitcnt lgkmcnt(14)
	s_add_u32 s14, s12, 0x1000
	s_addc_u32 s15, s13, 0
	global_store_dwordx4 v248, v[6:9], s[14:15]
	s_waitcnt lgkmcnt(13)
	s_add_u32 s14, s12, 0x2000
	s_addc_u32 s15, s13, 0
	global_store_dwordx4 v248, v[10:13], s[14:15]
	s_waitcnt lgkmcnt(12)
	s_add_u32 s14, s12, 0x3000
	s_addc_u32 s15, s13, 0
	global_store_dwordx4 v248, v[14:17], s[14:15]
	s_waitcnt lgkmcnt(11)
	s_add_u32 s14, s12, 0x4000
	s_addc_u32 s15, s13, 0
	global_store_dwordx4 v248, v[18:21], s[14:15]
	s_waitcnt lgkmcnt(10)
	s_add_u32 s14, s12, 0x5000
	s_addc_u32 s15, s13, 0
	global_store_dwordx4 v248, v[22:25], s[14:15]
	s_waitcnt lgkmcnt(9)
	s_add_u32 s14, s12, 0x6000
	s_addc_u32 s15, s13, 0
	global_store_dwordx4 v248, v[26:29], s[14:15]
	s_waitcnt lgkmcnt(8)
	s_add_u32 s14, s12, 0x7000
	s_addc_u32 s15, s13, 0
	global_store_dwordx4 v248, v[30:33], s[14:15]
	s_waitcnt lgkmcnt(7)
	s_add_u32 s14, s12, 0x8000
	s_addc_u32 s15, s13, 0
	global_store_dwordx4 v248, v[34:37], s[14:15]
	s_waitcnt lgkmcnt(6)
	s_add_u32 s14, s12, 0x9000
	s_addc_u32 s15, s13, 0
	global_store_dwordx4 v248, v[38:41], s[14:15]
	s_waitcnt lgkmcnt(5)
	s_add_u32 s14, s12, 0xa000
	s_addc_u32 s15, s13, 0
	global_store_dwordx4 v248, v[42:45], s[14:15]
	s_waitcnt lgkmcnt(4)
	s_add_u32 s14, s12, 0xb000
	s_addc_u32 s15, s13, 0
	global_store_dwordx4 v248, v[46:49], s[14:15]
	s_waitcnt lgkmcnt(3)
	s_add_u32 s14, s12, 0xc000
	s_addc_u32 s15, s13, 0
	global_store_dwordx4 v248, v[50:53], s[14:15]
	s_waitcnt lgkmcnt(2)
	s_add_u32 s14, s12, 0xd000
	s_addc_u32 s15, s13, 0
	global_store_dwordx4 v248, v[54:57], s[14:15]
	s_waitcnt lgkmcnt(1)
	s_add_u32 s14, s12, 0xe000
	s_addc_u32 s15, s13, 0
	global_store_dwordx4 v248, v[58:61], s[14:15]
	s_waitcnt lgkmcnt(0)
	s_add_u32 s14, s12, 0xf000
	s_addc_u32 s15, s13, 0
	global_store_dwordx4 v248, v[62:65], s[14:15]
	s_branch .LBB0_561
